# best variant + second pass of DPP adds over the remaining P6 block-mean butterfly steps (9 more ds_bpermute round trips removed)
# baseline (speedup 1.0000x reference)
; __device__ __forceinline__ unsigned pkh(float lo, float hi) { f32x2 v = {lo, hi}; h16x2 h = __builtin_convertvector(v, h16x2); return __builtin_bit_cast(unsigned, h); }
;     __device__ __forceinline__ void operator()(f32x4 (&acc)[2][2][4][2], const Unit& u, const Order& S, int wr, int wc, int fr_, int fq_, LAS unsigned char*, int) const {
;     ...
;                 for (int bj = 0; bj < 2; ++bj) {
;                     const f32x4 a = v[bj][0] * rn * gv[bj][0], b = v[bj][1] * rn * gv[bj][1];
;                     ks[bj][0] += a; ks[bj][1] += b;
;                     u32x4 w; w.x = pkh(a[0], a[1]); w.y = pkh(a[2], a[3]); w.z = pkh(b[0], b[1]); w.w = pkh(b[2], b[3]);
;                     *(u32x4*)(P + (size_t)row * NB + colh + 32 * bj + 8 * fq) = w;
;                 }
;             }
;         if (isk && !dry) {
;             const int b = u.pm / NBLK, blk = u.pm % NBLK, h = (u.pn - 3) * 4 + wc;
;             float* dst = kmean + ((size_t)(b * MOBA_H + h) * NBLK + blk) * HD;
; #pragma unroll
;             for (int bj = 0; bj < 2; ++bj)
; #pragma unroll
;                 for (int n = 0; n < 2; ++n)
; #pragma unroll
;                     for (int e = 0; e < 4; ++e) {
;                         float s = ks[bj][n][e];
;                         s += __shfl_xor(s, 1); s += __shfl_xor(s, 2); s += __shfl_xor(s, 4); s += __shfl_xor(s, 8);
;                         if (fr == 0) atomicAdd(dst + 32 * bj + 8 * fq + 4 * n + e, s);
;                     }
.LBB0_777:
	v_add_u32_e32 v143, 0xb0, v178
	v_pk_mul_f32 v[34:35], v[152:153], v[142:143] op_sel_hi:[1,0]
	v_pk_mul_f32 v[36:37], v[154:155], v[142:143] op_sel_hi:[1,0]
	v_pk_mul_f32 v[38:39], v[8:9], v[34:35]
	v_pk_mul_f32 v[8:9], v[48:49], v[142:143] op_sel_hi:[1,0]
	v_pk_mul_f32 v[6:7], v[6:7], v[36:37]
	v_pk_mul_f32 v[34:35], v[4:5], v[8:9]
	v_mov_b64_e32 v[8:9], s[58:59]
	v_pk_mul_f32 v[36:37], v[144:145], v[142:143] op_sel_hi:[1,0]
	v_mad_i64_i32 v[8:9], s[2:3], v143, s51, v[8:9]
	v_pk_mul_f32 v[36:37], v[2:3], v[36:37]
	v_lshl_add_u64 v[8:9], s[26:27], 1, v[8:9]
	v_cvt_pk_f16_f32 v2, v6, v7
	v_cvt_pk_f16_f32 v3, v38, v39
	v_cvt_pk_f16_f32 v4, v36, v37
	v_cvt_pk_f16_f32 v5, v34, v35
	v_lshl_add_u64 v[48:49], v[24:25], 1, v[8:9]
	global_store_dwordx4 v[48:49], v[2:5], off
	s_andn2_b64 vcc, exec, s[24:25]
	s_nop 0
	v_pk_mul_f32 v[2:3], v[44:45], v[142:143] op_sel_hi:[1,0]
	v_pk_mul_f32 v[4:5], v[46:47], v[142:143] op_sel_hi:[1,0]
	v_pk_mul_f32 v[8:9], v[16:17], v[2:3]
	v_pk_mul_f32 v[14:15], v[14:15], v[4:5]
	v_pk_mul_f32 v[2:3], v[40:41], v[142:143] op_sel_hi:[1,0]
	v_pk_mul_f32 v[4:5], v[42:43], v[142:143] op_sel_hi:[1,0]
	v_pk_mul_f32 v[2:3], v[12:13], v[2:3]
	v_pk_mul_f32 v[4:5], v[10:11], v[4:5]
	v_cvt_pk_f16_f32 v10, v14, v15
	v_cvt_pk_f16_f32 v11, v8, v9
	v_cvt_pk_f16_f32 v12, v4, v5
	v_cvt_pk_f16_f32 v13, v2, v3
	global_store_dwordx4 v[48:49], v[10:13], off offset:64
	s_cbranch_vccnz .LBB0_811
	s_nop 0
	v_pk_add_f32 v[10:11], v[150:151], 0 op_sel_hi:[1,0]
	v_xor_b32_e32 v13, 2, v193
	v_pk_add_f32 v[10:11], v[10:11], v[140:141]
	v_xor_b32_e32 v16, 4, v193
	v_pk_add_f32 v[10:11], v[10:11], v[128:129]
	s_ashr_i32 s2, s53, 31
	v_pk_add_f32 v[10:11], v[10:11], v[112:113]
	s_lshr_b32 s2, s2, 26
	v_pk_add_f32 v[10:11], v[10:11], v[96:97]
	s_add_i32 s2, s53, s2
	v_pk_add_f32 v[10:11], v[10:11], v[80:81]
	s_ashr_i32 s3, s2, 6
	v_pk_add_f32 v[10:11], v[10:11], v[64:65]
	s_lshl_b32 s17, s22, 2
	v_pk_add_f32 v[10:11], v[10:11], v[6:7]
	v_and_b32_e32 v7, 64, v193
	v_xor_b32_e32 v6, 1, v193
	v_add_u32_e32 v7, 64, v7
	v_cmp_lt_i32_e32 vcc, v6, v7
	s_mul_i32 s3, s3, 12
	s_add_i32 s17, s47, s17
	v_cndmask_b32_e32 v6, v193, v6, vcc
	v_lshlrev_b32_e32 v12, 2, v6
	v_cmp_lt_i32_e32 vcc, v13, v7
	v_xor_b32_e32 v17, 8, v193
	s_andn2_b32 s2, s2, 63
	v_cndmask_b32_e32 v13, v193, v13, vcc
	v_lshlrev_b32_e32 v13, 2, v13
	s_waitcnt lgkmcnt(0)
	s_nop 1
	v_add_f32_dpp v6, v10, v10 quad_perm:[1,0,3,2] row_mask:0xf bank_mask:0xf
	v_cmp_lt_i32_e32 vcc, v16, v7
	s_add_i32 s24, s17, s3
	s_sub_i32 s2, s53, s2
	v_cndmask_b32_e32 v16, v193, v16, vcc
	v_lshlrev_b32_e32 v16, 2, v16
	s_waitcnt lgkmcnt(0)
	s_nop 1
	v_add_f32_dpp v6, v6, v6 quad_perm:[2,3,0,1] row_mask:0xf bank_mask:0xf
	v_cmp_lt_i32_e32 vcc, v17, v7
	s_ashr_i32 s25, s24, 31
	s_ashr_i32 s3, s2, 31
	v_cndmask_b32_e32 v7, v193, v17, vcc
	s_lshl_b64 s[24:25], s[24:25], 14
	v_lshlrev_b32_e32 v17, 2, v7
	s_waitcnt lgkmcnt(0)
	s_nop 1
	v_add_f32_dpp v10, v6, v6 row_half_mirror row_mask:0xf bank_mask:0xf
	s_add_u32 s17, s6, s24
	ds_bpermute_b32 v40, v17, v10
	s_addc_u32 s22, s7, s25
	s_lshl_b64 s[2:3], s[2:3], 8
	s_add_u32 s2, s17, s2
	s_addc_u32 s3, s22, s3
	v_cmp_eq_u32_e32 vcc, 0, v182
	v_lshl_add_u64 v[6:7], v[24:25], 2, s[2:3]
	s_and_saveexec_b64 s[2:3], vcc
	s_cbranch_execz .LBB0_780
	s_waitcnt lgkmcnt(0)
	v_add_f32_e32 v10, v10, v40
	global_atomic_add_f32 v[6:7], v10, off
.LBB0_780:
	s_or_b64 exec, exec, s[2:3]
	s_nop 1
	v_add_f32_dpp v10, v11, v11 quad_perm:[1,0,3,2] row_mask:0xf bank_mask:0xf
	s_waitcnt lgkmcnt(0)
	s_nop 1
	v_add_f32_dpp v24, v10, v10 quad_perm:[2,3,0,1] row_mask:0xf bank_mask:0xf
	v_pk_add_f32 v[10:11], v[148:149], 0 op_sel_hi:[1,0]
	s_waitcnt lgkmcnt(0)
	s_nop 1
	v_add_f32_dpp v24, v24, v24 row_half_mirror row_mask:0xf bank_mask:0xf
	v_pk_add_f32 v[10:11], v[10:11], v[138:139]
	ds_bpermute_b32 v25, v17, v24
	v_pk_add_f32 v[10:11], v[10:11], v[126:127]
	s_nop 0
	v_pk_add_f32 v[10:11], v[10:11], v[110:111]
	s_nop 0
	v_pk_add_f32 v[10:11], v[10:11], v[94:95]
	s_nop 0
	v_pk_add_f32 v[10:11], v[10:11], v[78:79]
	s_nop 0
	v_pk_add_f32 v[10:11], v[10:11], v[62:63]
	s_nop 0
	v_pk_add_f32 v[10:11], v[10:11], v[38:39]
	s_and_saveexec_b64 s[2:3], vcc
	s_cbranch_execz .LBB0_782
	s_waitcnt lgkmcnt(0)
	v_add_f32_e32 v24, v24, v25
	global_atomic_add_f32 v[6:7], v24, off offset:4

; __device__ __forceinline__ unsigned pkh(float lo, float hi) { f32x2 v = {lo, hi}; h16x2 h = __builtin_convertvector(v, h16x2); return __builtin_bit_cast(unsigned, h); }
;     __device__ __forceinline__ void operator()(f32x4 (&acc)[2][2][4][2], const Unit& u, const Order& S, int wr, int wc, int fr_, int fq_, LAS unsigned char*, int) const {
;     ...
;                     const f32x4 a = v[bj][0] * rn * gv[bj][0], b = v[bj][1] * rn * gv[bj][1];
;                     ks[bj][0] += a; ks[bj][1] += b;
;                     u32x4 w; w.x = pkh(a[0], a[1]); w.y = pkh(a[2], a[3]); w.z = pkh(b[0], b[1]); w.w = pkh(b[2], b[3]);
;                     *(u32x4*)(P + (size_t)row * NB + colh + 32 * bj + 8 * fq) = w;
;                 }
;             }
;         if (isk && !dry) {
;             const int b = u.pm / NBLK, blk = u.pm % NBLK, h = (u.pn - 3) * 4 + wc;
;             float* dst = kmean + ((size_t)(b * MOBA_H + h) * NBLK + blk) * HD;
; #pragma unroll
;             for (int bj = 0; bj < 2; ++bj)
; #pragma unroll
;                 for (int n = 0; n < 2; ++n)
; #pragma unroll
;                     for (int e = 0; e < 4; ++e) {
;                         float s = ks[bj][n][e];
;                         s += __shfl_xor(s, 1); s += __shfl_xor(s, 2); s += __shfl_xor(s, 4); s += __shfl_xor(s, 8);
;                         if (fr == 0) atomicAdd(dst + 32 * bj + 8 * fq + 4 * n + e, s);
.LBB0_788:
	s_or_b64 exec, exec, s[2:3]
	s_nop 1
	v_add_f32_dpp v10, v11, v11 quad_perm:[1,0,3,2] row_mask:0xf bank_mask:0xf
	s_waitcnt lgkmcnt(0)
	s_nop 1
	v_add_f32_dpp v24, v10, v10 quad_perm:[2,3,0,1] row_mask:0xf bank_mask:0xf
	v_pk_add_f32 v[10:11], v[32:33], 0 op_sel_hi:[1,0]
	s_waitcnt lgkmcnt(0)
	s_nop 1
	v_add_f32_dpp v24, v24, v24 row_half_mirror row_mask:0xf bank_mask:0xf
	v_pk_add_f32 v[10:11], v[10:11], v[134:135]
	ds_bpermute_b32 v25, v17, v24
	v_pk_add_f32 v[10:11], v[10:11], v[122:123]
	s_nop 0
	v_pk_add_f32 v[10:11], v[10:11], v[106:107]
	s_nop 0
	v_pk_add_f32 v[10:11], v[10:11], v[90:91]
	s_nop 0
	v_pk_add_f32 v[10:11], v[10:11], v[74:75]
	s_nop 0
	v_pk_add_f32 v[10:11], v[10:11], v[58:59]
	s_nop 0
	v_pk_add_f32 v[10:11], v[10:11], v[34:35]
	s_and_saveexec_b64 s[2:3], vcc
	s_cbranch_execz .LBB0_790
	s_waitcnt lgkmcnt(0)
	v_add_f32_e32 v24, v24, v25
	global_atomic_add_f32 v[6:7], v24, off offset:20

; __device__ __forceinline__ unsigned pkh(float lo, float hi) { f32x2 v = {lo, hi}; h16x2 h = __builtin_convertvector(v, h16x2); return __builtin_bit_cast(unsigned, h); }
;     __device__ __forceinline__ void operator()(f32x4 (&acc)[2][2][4][2], const Unit& u, const Order& S, int wr, int wc, int fr_, int fq_, LAS unsigned char*, int) const {
;     ...
;                     const f32x4 a = v[bj][0] * rn * gv[bj][0], b = v[bj][1] * rn * gv[bj][1];
;                     ks[bj][0] += a; ks[bj][1] += b;
;                     u32x4 w; w.x = pkh(a[0], a[1]); w.y = pkh(a[2], a[3]); w.z = pkh(b[0], b[1]); w.w = pkh(b[2], b[3]);
;                     *(u32x4*)(P + (size_t)row * NB + colh + 32 * bj + 8 * fq) = w;
;                 }
;             }
;         if (isk && !dry) {
;             const int b = u.pm / NBLK, blk = u.pm % NBLK, h = (u.pn - 3) * 4 + wc;
;             float* dst = kmean + ((size_t)(b * MOBA_H + h) * NBLK + blk) * HD;
; #pragma unroll
;             for (int bj = 0; bj < 2; ++bj)
; #pragma unroll
;                 for (int n = 0; n < 2; ++n)
; #pragma unroll
;                     for (int e = 0; e < 4; ++e) {
;                         float s = ks[bj][n][e];
;                         s += __shfl_xor(s, 1); s += __shfl_xor(s, 2); s += __shfl_xor(s, 4); s += __shfl_xor(s, 8);
;                         if (fr == 0) atomicAdd(dst + 32 * bj + 8 * fq + 4 * n + e, s);
.LBB0_796:
	s_or_b64 exec, exec, s[2:3]
	s_nop 1
	v_add_f32_dpp v10, v11, v11 quad_perm:[1,0,3,2] row_mask:0xf bank_mask:0xf
	s_waitcnt lgkmcnt(0)
	s_nop 1
	v_add_f32_dpp v24, v10, v10 quad_perm:[2,3,0,1] row_mask:0xf bank_mask:0xf
	ds_bpermute_b32 v25, v16, v24
	v_pk_add_f32 v[10:11], v[22:23], 0 op_sel_hi:[1,0]
	s_nop 0
	v_pk_add_f32 v[10:11], v[10:11], v[130:131]
	s_nop 0
	v_pk_add_f32 v[10:11], v[10:11], v[118:119]
	s_nop 0
	v_pk_add_f32 v[14:15], v[10:11], v[102:103]
	s_waitcnt lgkmcnt(0)
	v_add_f32_e32 v10, v24, v25
	ds_bpermute_b32 v11, v17, v10
	v_pk_add_f32 v[14:15], v[14:15], v[86:87]
	s_nop 0
	v_pk_add_f32 v[14:15], v[14:15], v[70:71]
	s_nop 0
	v_pk_add_f32 v[14:15], v[14:15], v[54:55]
	s_nop 0
	v_pk_add_f32 v[8:9], v[14:15], v[8:9]
	s_and_saveexec_b64 s[2:3], vcc
	s_cbranch_execz .LBB0_798
	s_waitcnt lgkmcnt(0)
	v_add_f32_e32 v10, v10, v11
	global_atomic_add_f32 v[6:7], v10, off offset:132

; __device__ __forceinline__ unsigned pkh(float lo, float hi) { f32x2 v = {lo, hi}; h16x2 h = __builtin_convertvector(v, h16x2); return __builtin_bit_cast(unsigned, h); }
;     __device__ __forceinline__ void operator()(f32x4 (&acc)[2][2][4][2], const Unit& u, const Order& S, int wr, int wc, int fr_, int fq_, LAS unsigned char*, int) const {
;     ...
;                     const f32x4 a = v[bj][0] * rn * gv[bj][0], b = v[bj][1] * rn * gv[bj][1];
;                     ks[bj][0] += a; ks[bj][1] += b;
;                     u32x4 w; w.x = pkh(a[0], a[1]); w.y = pkh(a[2], a[3]); w.z = pkh(b[0], b[1]); w.w = pkh(b[2], b[3]);
;                     *(u32x4*)(P + (size_t)row * NB + colh + 32 * bj + 8 * fq) = w;
;                 }
;             }
;         if (isk && !dry) {
;             const int b = u.pm / NBLK, blk = u.pm % NBLK, h = (u.pn - 3) * 4 + wc;
;             float* dst = kmean + ((size_t)(b * MOBA_H + h) * NBLK + blk) * HD;
; #pragma unroll
;             for (int bj = 0; bj < 2; ++bj)
; #pragma unroll
;                 for (int n = 0; n < 2; ++n)
; #pragma unroll
;                     for (int e = 0; e < 4; ++e) {
;                         float s = ks[bj][n][e];
;                         s += __shfl_xor(s, 1); s += __shfl_xor(s, 2); s += __shfl_xor(s, 4); s += __shfl_xor(s, 8);
;                         if (fr == 0) atomicAdd(dst + 32 * bj + 8 * fq + 4 * n + e, s);
.LBB0_804:
	s_or_b64 exec, exec, s[2:3]
	s_nop 1
	v_add_f32_dpp v4, v5, v5 quad_perm:[1,0,3,2] row_mask:0xf bank_mask:0xf
	s_waitcnt lgkmcnt(0)
	s_nop 1
	v_add_f32_dpp v10, v4, v4 quad_perm:[2,3,0,1] row_mask:0xf bank_mask:0xf
	ds_bpermute_b32 v11, v16, v10
	v_pk_add_f32 v[4:5], v[18:19], 0 op_sel_hi:[1,0]
	s_nop 0
	v_pk_add_f32 v[4:5], v[4:5], v[26:27]
	s_nop 0
	v_pk_add_f32 v[4:5], v[4:5], v[114:115]
	s_nop 0
	v_pk_add_f32 v[8:9], v[4:5], v[98:99]
	s_waitcnt lgkmcnt(0)
	v_add_f32_e32 v4, v10, v11
	ds_bpermute_b32 v5, v17, v4
	v_pk_add_f32 v[8:9], v[8:9], v[82:83]
	s_nop 0
	v_pk_add_f32 v[8:9], v[8:9], v[66:67]
	s_nop 0
	v_pk_add_f32 v[8:9], v[8:9], v[50:51]
	s_nop 0
	v_pk_add_f32 v[2:3], v[8:9], v[2:3]
	s_and_saveexec_b64 s[2:3], vcc
	s_cbranch_execz .LBB0_806
	s_waitcnt lgkmcnt(0)
	v_add_f32_e32 v4, v4, v5
	global_atomic_add_f32 v[6:7], v4, off offset:148
